# scalar-side LDS-DMA addressing extended to the QG / Q2 / gate K-loops (half-tile add moved in place to the A base so the B base survives)
# speedup vs baseline: 1.0093x; 1.0076x over previous
.LBB0_673:
	s_add_u32 s23, s54, 0xfffc0080
	s_addc_u32 s24, s55, -1
	s_add_i32 s26, 0, 0x10000
	s_cmp_eq_u32 s21, 12
	s_cselect_b32 s57, s15, s24
	s_cselect_b32 s56, s16, s23
	v_add_u32_e32 v149, s26, v147
	s_cselect_b32 s25, s17, s20
	s_cselect_b32 s24, s18, s19
	s_add_i32 s23, 0, 0x14000
	ds_read_b128 v[150:153], v149
	ds_read_b128 v[184:187], v149 offset:1024
	ds_read_b128 v[188:191], v149 offset:2048
	ds_read_b128 v[192:195], v149 offset:3072
	v_add_u32_e32 v149, s23, v147
	ds_read_b128 v[196:199], v149
	ds_read_b128 v[200:203], v149 offset:1024
	ds_read_b128 v[204:207], v149 offset:2048
	ds_read_b128 v[208:211], v149 offset:3072
	s_add_i32 m0, s1, 0xc000
	ds_read_b128 v[212:215], v148
	ds_read_b128 v[216:219], v148 offset:1024
	ds_read_b128 v[220:223], v148 offset:2048
	ds_read_b128 v[224:227], v148 offset:3072
	ds_read_b128 v[228:231], v148 offset:4096
	ds_read_b128 v[232:235], v148 offset:5120
	ds_read_b128 v[236:239], v148 offset:6144
	ds_read_b128 v[240:243], v148 offset:7168
	global_load_lds_dwordx4 v142, s[54:55]
	s_add_i32 m0, s1, 0xe000
	s_nop 0
	global_load_lds_dwordx4 v144, s[54:55]
	s_waitcnt vmcnt(8)
	s_waitcnt lgkmcnt(0)
	v_mfma_f32_16x16x32_f16 v[128:131], v[150:153], v[212:215], v[128:131]
	v_mfma_f32_16x16x32_f16 v[124:127], v[188:191], v[212:215], v[124:127]
	v_mfma_f32_16x16x32_f16 v[120:123], v[150:153], v[220:223], v[120:123]
	v_mfma_f32_16x16x32_f16 v[112:115], v[188:191], v[220:223], v[112:115]
	s_barrier
	s_setprio 1
	s_waitcnt lgkmcnt(0)
	v_mfma_f32_16x16x32_f16 v[104:107], v[150:153], v[228:231], v[104:107]
	v_mfma_f32_16x16x32_f16 v[100:103], v[188:191], v[228:231], v[100:103]
	v_mfma_f32_16x16x32_f16 v[88:91], v[150:153], v[236:239], v[88:91]
	v_mfma_f32_16x16x32_f16 v[84:87], v[188:191], v[236:239], v[84:87]
	v_mfma_f32_16x16x32_f16 v[128:131], v[184:187], v[216:219], v[128:131]
	v_mfma_f32_16x16x32_f16 v[124:127], v[192:195], v[216:219], v[124:127]
	v_mfma_f32_16x16x32_f16 v[120:123], v[184:187], v[224:227], v[120:123]
	v_mfma_f32_16x16x32_f16 v[112:115], v[192:195], v[224:227], v[112:115]
	v_mfma_f32_16x16x32_f16 v[104:107], v[184:187], v[232:235], v[104:107]
	v_mfma_f32_16x16x32_f16 v[100:103], v[192:195], v[232:235], v[100:103]
	v_mfma_f32_16x16x32_f16 v[88:91], v[184:187], v[240:243], v[88:91]
	v_mfma_f32_16x16x32_f16 v[84:87], v[192:195], v[240:243], v[84:87]
	s_setprio 0
	s_setprio 1
	v_mfma_f32_16x16x32_f16 v[116:119], v[196:199], v[212:215], v[116:119]
	v_mfma_f32_16x16x32_f16 v[108:111], v[204:207], v[212:215], v[108:111]
	v_mfma_f32_16x16x32_f16 v[96:99], v[196:199], v[220:223], v[96:99]
	v_mfma_f32_16x16x32_f16 v[92:95], v[204:207], v[220:223], v[92:95]
	v_mfma_f32_16x16x32_f16 v[80:83], v[196:199], v[228:231], v[80:83]
	v_mfma_f32_16x16x32_f16 v[76:79], v[204:207], v[228:231], v[76:79]
	v_mfma_f32_16x16x32_f16 v[72:75], v[196:199], v[236:239], v[72:75]
	v_mfma_f32_16x16x32_f16 v[68:71], v[204:207], v[236:239], v[68:71]
	v_mfma_f32_16x16x32_f16 v[116:119], v[200:203], v[216:219], v[116:119]
	v_mfma_f32_16x16x32_f16 v[108:111], v[208:211], v[216:219], v[108:111]
	v_mfma_f32_16x16x32_f16 v[96:99], v[200:203], v[224:227], v[96:99]
	v_mfma_f32_16x16x32_f16 v[92:95], v[208:211], v[224:227], v[92:95]
	v_mfma_f32_16x16x32_f16 v[80:83], v[200:203], v[232:235], v[80:83]
	v_mfma_f32_16x16x32_f16 v[76:79], v[208:211], v[232:235], v[76:79]
	v_mfma_f32_16x16x32_f16 v[72:75], v[200:203], v[240:243], v[72:75]
	v_mfma_f32_16x16x32_f16 v[68:71], v[208:211], v[240:243], v[68:71]
	s_setprio 0
	s_barrier
	s_add_i32 s26, s26, s0
	s_mov_b32 m0, s26
	ds_read_b128 v[212:215], v148 offset:16384
	ds_read_b128 v[216:219], v148 offset:17408
	ds_read_b128 v[220:223], v148 offset:18432
	ds_read_b128 v[224:227], v148 offset:19456
	ds_read_b128 v[228:231], v148 offset:20480
	ds_read_b128 v[232:235], v148 offset:21504
	ds_read_b128 v[236:239], v148 offset:22528
	ds_read_b128 v[240:243], v148 offset:23552
	global_load_lds_dwordx4 v136, s[24:25]
	s_add_i32 m0, s26, 0x2000
	s_add_i32 s23, s23, s0
	global_load_lds_dwordx4 v0, s[24:25]
	s_mov_b32 m0, s23
	s_nop 0
	global_load_lds_dwordx4 v138, s[24:25]
	s_add_i32 m0, s23, 0x2000
	s_nop 0
	global_load_lds_dwordx4 v132, s[24:25]
	s_mov_b32 m0, s1
	s_nop 0
	global_load_lds_dwordx4 v140, s[56:57]
	s_mov_b32 m0, s2
	s_nop 0
	global_load_lds_dwordx4 v134, s[56:57]
	s_waitcnt vmcnt(8)
	s_waitcnt lgkmcnt(0)
	v_mfma_f32_16x16x32_f16 v[64:67], v[150:153], v[212:215], v[64:67]
	v_mfma_f32_16x16x32_f16 v[60:63], v[188:191], v[212:215], v[60:63]
	v_mfma_f32_16x16x32_f16 v[56:59], v[150:153], v[220:223], v[56:59]
	v_mfma_f32_16x16x32_f16 v[52:55], v[188:191], v[220:223], v[52:55]
	s_barrier
	s_setprio 1
	s_waitcnt lgkmcnt(0)
	v_mfma_f32_16x16x32_f16 v[40:43], v[150:153], v[228:231], v[40:43]
	v_mfma_f32_16x16x32_f16 v[36:39], v[188:191], v[228:231], v[36:39]
	v_mfma_f32_16x16x32_f16 v[24:27], v[150:153], v[236:239], v[24:27]
	v_mfma_f32_16x16x32_f16 v[20:23], v[188:191], v[236:239], v[20:23]
	v_mfma_f32_16x16x32_f16 v[64:67], v[184:187], v[216:219], v[64:67]
	v_mfma_f32_16x16x32_f16 v[60:63], v[192:195], v[216:219], v[60:63]
	v_mfma_f32_16x16x32_f16 v[56:59], v[184:187], v[224:227], v[56:59]
	v_mfma_f32_16x16x32_f16 v[52:55], v[192:195], v[224:227], v[52:55]
	v_mfma_f32_16x16x32_f16 v[40:43], v[184:187], v[232:235], v[40:43]
	v_mfma_f32_16x16x32_f16 v[36:39], v[192:195], v[232:235], v[36:39]
	v_mfma_f32_16x16x32_f16 v[24:27], v[184:187], v[240:243], v[24:27]
	v_mfma_f32_16x16x32_f16 v[20:23], v[192:195], v[240:243], v[20:23]
	s_setprio 0
	s_setprio 1
	v_mfma_f32_16x16x32_f16 v[48:51], v[196:199], v[212:215], v[48:51]
	v_mfma_f32_16x16x32_f16 v[44:47], v[204:207], v[212:215], v[44:47]
	v_mfma_f32_16x16x32_f16 v[32:35], v[196:199], v[220:223], v[32:35]
	v_mfma_f32_16x16x32_f16 v[28:31], v[204:207], v[220:223], v[28:31]
	v_mfma_f32_16x16x32_f16 v[16:19], v[196:199], v[228:231], v[16:19]
	v_mfma_f32_16x16x32_f16 v[12:15], v[204:207], v[228:231], v[12:15]
	v_mfma_f32_16x16x32_f16 v[8:11], v[196:199], v[236:239], v[8:11]
	v_mfma_f32_16x16x32_f16 v[4:7], v[204:207], v[236:239], v[4:7]
	v_mfma_f32_16x16x32_f16 v[48:51], v[200:203], v[216:219], v[48:51]
	v_mfma_f32_16x16x32_f16 v[44:47], v[208:211], v[216:219], v[44:47]
	v_mfma_f32_16x16x32_f16 v[32:35], v[200:203], v[224:227], v[32:35]
	v_mfma_f32_16x16x32_f16 v[28:31], v[208:211], v[224:227], v[28:31]
	v_mfma_f32_16x16x32_f16 v[16:19], v[200:203], v[232:235], v[16:19]
	v_mfma_f32_16x16x32_f16 v[12:15], v[208:211], v[232:235], v[12:15]
	v_mfma_f32_16x16x32_f16 v[8:11], v[200:203], v[240:243], v[8:11]
	v_mfma_f32_16x16x32_f16 v[4:7], v[208:211], v[240:243], v[4:7]
	s_setprio 0
	s_barrier
	s_add_i32 s23, 0, 0x18000
	v_add_u32_e32 v149, s23, v147
	s_add_i32 s26, 0, 0x1c000
	ds_read_b128 v[150:153], v149
	ds_read_b128 v[184:187], v149 offset:1024
	ds_read_b128 v[188:191], v149 offset:2048
	ds_read_b128 v[192:195], v149 offset:3072
	v_add_u32_e32 v149, s26, v147
	ds_read_b128 v[196:199], v149
	ds_read_b128 v[200:203], v149 offset:1024
	ds_read_b128 v[204:207], v149 offset:2048
	ds_read_b128 v[208:211], v149 offset:3072
	s_add_u32 s56, s56, 0x40000
	s_addc_u32 s57, s57, 0
	s_mov_b32 m0, s3
	ds_read_b128 v[212:215], v148 offset:32768
	ds_read_b128 v[216:219], v148 offset:33792
	ds_read_b128 v[220:223], v148 offset:34816
	ds_read_b128 v[224:227], v148 offset:35840
	ds_read_b128 v[228:231], v148 offset:36864
	ds_read_b128 v[232:235], v148 offset:37888
	ds_read_b128 v[236:239], v148 offset:38912
	ds_read_b128 v[240:243], v148 offset:39936
	global_load_lds_dwordx4 v140, s[56:57]
	s_mov_b32 m0, s4
	s_nop 0
	global_load_lds_dwordx4 v134, s[56:57]
	s_waitcnt vmcnt(8)
	s_waitcnt lgkmcnt(0)
	v_mfma_f32_16x16x32_f16 v[128:131], v[150:153], v[212:215], v[128:131]
	v_mfma_f32_16x16x32_f16 v[124:127], v[188:191], v[212:215], v[124:127]
	v_mfma_f32_16x16x32_f16 v[120:123], v[150:153], v[220:223], v[120:123]
	v_mfma_f32_16x16x32_f16 v[112:115], v[188:191], v[220:223], v[112:115]
	s_barrier
	s_setprio 1
	s_waitcnt lgkmcnt(0)
	v_mfma_f32_16x16x32_f16 v[104:107], v[150:153], v[228:231], v[104:107]
	v_mfma_f32_16x16x32_f16 v[100:103], v[188:191], v[228:231], v[100:103]
	v_mfma_f32_16x16x32_f16 v[88:91], v[150:153], v[236:239], v[88:91]
	v_mfma_f32_16x16x32_f16 v[84:87], v[188:191], v[236:239], v[84:87]
	v_mfma_f32_16x16x32_f16 v[128:131], v[184:187], v[216:219], v[128:131]
	v_mfma_f32_16x16x32_f16 v[124:127], v[192:195], v[216:219], v[124:127]
	v_mfma_f32_16x16x32_f16 v[120:123], v[184:187], v[224:227], v[120:123]
	v_mfma_f32_16x16x32_f16 v[112:115], v[192:195], v[224:227], v[112:115]
	v_mfma_f32_16x16x32_f16 v[104:107], v[184:187], v[232:235], v[104:107]
	v_mfma_f32_16x16x32_f16 v[100:103], v[192:195], v[232:235], v[100:103]
	v_mfma_f32_16x16x32_f16 v[88:91], v[184:187], v[240:243], v[88:91]
	v_mfma_f32_16x16x32_f16 v[84:87], v[192:195], v[240:243], v[84:87]
	s_setprio 0
	s_setprio 1
	v_mfma_f32_16x16x32_f16 v[116:119], v[196:199], v[212:215], v[116:119]
	v_mfma_f32_16x16x32_f16 v[108:111], v[204:207], v[212:215], v[108:111]
	v_mfma_f32_16x16x32_f16 v[96:99], v[196:199], v[220:223], v[96:99]
	v_mfma_f32_16x16x32_f16 v[92:95], v[204:207], v[220:223], v[92:95]
	v_mfma_f32_16x16x32_f16 v[80:83], v[196:199], v[228:231], v[80:83]
	v_mfma_f32_16x16x32_f16 v[76:79], v[204:207], v[228:231], v[76:79]
	v_mfma_f32_16x16x32_f16 v[72:75], v[196:199], v[236:239], v[72:75]
	v_mfma_f32_16x16x32_f16 v[68:71], v[204:207], v[236:239], v[68:71]
	v_mfma_f32_16x16x32_f16 v[116:119], v[200:203], v[216:219], v[116:119]
	v_mfma_f32_16x16x32_f16 v[108:111], v[208:211], v[216:219], v[108:111]
	v_mfma_f32_16x16x32_f16 v[96:99], v[200:203], v[224:227], v[96:99]
	v_mfma_f32_16x16x32_f16 v[92:95], v[208:211], v[224:227], v[92:95]
	v_mfma_f32_16x16x32_f16 v[80:83], v[200:203], v[232:235], v[80:83]
	v_mfma_f32_16x16x32_f16 v[76:79], v[208:211], v[232:235], v[76:79]
	v_mfma_f32_16x16x32_f16 v[72:75], v[200:203], v[240:243], v[72:75]
	v_mfma_f32_16x16x32_f16 v[68:71], v[208:211], v[240:243], v[68:71]
	s_setprio 0
	s_barrier
	s_add_i32 s23, s23, s0
	s_add_u32 s24, s24, 0x80
	s_addc_u32 s25, s25, 0
	s_add_u32 s56, s56, 0xfffc0080
	s_addc_u32 s57, s57, -1
	s_mov_b32 m0, s23
	ds_read_b128 v[212:215], v148 offset:49152
	ds_read_b128 v[216:219], v148 offset:50176
	ds_read_b128 v[220:223], v148 offset:51200
	ds_read_b128 v[224:227], v148 offset:52224
	ds_read_b128 v[228:231], v148 offset:53248
	ds_read_b128 v[232:235], v148 offset:54272
	ds_read_b128 v[236:239], v148 offset:55296
	ds_read_b128 v[240:243], v148 offset:56320
	global_load_lds_dwordx4 v136, s[24:25]
	s_add_i32 m0, s23, 0x2000
	s_add_i32 s23, s26, s0
	global_load_lds_dwordx4 v0, s[24:25]
	s_mov_b32 m0, s23
	s_nop 0
	global_load_lds_dwordx4 v138, s[24:25]
	s_add_i32 m0, s23, 0x2000
	s_nop 0
	global_load_lds_dwordx4 v132, s[24:25]
	s_mov_b32 m0, s10
	s_nop 0
	global_load_lds_dwordx4 v140, s[56:57]
	s_mov_b32 m0, s11
	s_nop 0
	global_load_lds_dwordx4 v134, s[56:57]
	s_waitcnt vmcnt(8)
	s_waitcnt lgkmcnt(0)
	v_mfma_f32_16x16x32_f16 v[64:67], v[150:153], v[212:215], v[64:67]
	v_mfma_f32_16x16x32_f16 v[60:63], v[188:191], v[212:215], v[60:63]
	v_mfma_f32_16x16x32_f16 v[56:59], v[150:153], v[220:223], v[56:59]
	v_mfma_f32_16x16x32_f16 v[52:55], v[188:191], v[220:223], v[52:55]
	s_barrier
	s_setprio 1
	s_waitcnt lgkmcnt(0)
	v_mfma_f32_16x16x32_f16 v[40:43], v[150:153], v[228:231], v[40:43]
	v_mfma_f32_16x16x32_f16 v[36:39], v[188:191], v[228:231], v[36:39]
	v_mfma_f32_16x16x32_f16 v[24:27], v[150:153], v[236:239], v[24:27]
	v_mfma_f32_16x16x32_f16 v[20:23], v[188:191], v[236:239], v[20:23]
	v_mfma_f32_16x16x32_f16 v[64:67], v[184:187], v[216:219], v[64:67]
	v_mfma_f32_16x16x32_f16 v[60:63], v[192:195], v[216:219], v[60:63]
	v_mfma_f32_16x16x32_f16 v[56:59], v[184:187], v[224:227], v[56:59]
	v_mfma_f32_16x16x32_f16 v[52:55], v[192:195], v[224:227], v[52:55]
	v_mfma_f32_16x16x32_f16 v[40:43], v[184:187], v[232:235], v[40:43]
	v_mfma_f32_16x16x32_f16 v[36:39], v[192:195], v[232:235], v[36:39]
	v_mfma_f32_16x16x32_f16 v[24:27], v[184:187], v[240:243], v[24:27]
	v_mfma_f32_16x16x32_f16 v[20:23], v[192:195], v[240:243], v[20:23]
	s_setprio 0
	s_setprio 1
	v_mfma_f32_16x16x32_f16 v[48:51], v[196:199], v[212:215], v[48:51]
	v_mfma_f32_16x16x32_f16 v[44:47], v[204:207], v[212:215], v[44:47]
	v_mfma_f32_16x16x32_f16 v[32:35], v[196:199], v[220:223], v[32:35]
	v_mfma_f32_16x16x32_f16 v[28:31], v[204:207], v[220:223], v[28:31]
	v_mfma_f32_16x16x32_f16 v[16:19], v[196:199], v[228:231], v[16:19]
	v_mfma_f32_16x16x32_f16 v[12:15], v[204:207], v[228:231], v[12:15]
	v_mfma_f32_16x16x32_f16 v[8:11], v[196:199], v[236:239], v[8:11]
	v_mfma_f32_16x16x32_f16 v[4:7], v[204:207], v[236:239], v[4:7]
	v_mfma_f32_16x16x32_f16 v[48:51], v[200:203], v[216:219], v[48:51]
	v_mfma_f32_16x16x32_f16 v[44:47], v[208:211], v[216:219], v[44:47]
	v_mfma_f32_16x16x32_f16 v[32:35], v[200:203], v[224:227], v[32:35]
	v_mfma_f32_16x16x32_f16 v[28:31], v[208:211], v[224:227], v[28:31]
	v_mfma_f32_16x16x32_f16 v[16:19], v[200:203], v[232:235], v[16:19]
	v_mfma_f32_16x16x32_f16 v[12:15], v[208:211], v[232:235], v[12:15]
	v_mfma_f32_16x16x32_f16 v[8:11], v[200:203], v[240:243], v[8:11]
	v_mfma_f32_16x16x32_f16 v[4:7], v[208:211], v[240:243], v[4:7]
	s_setprio 0
	s_barrier
	s_add_i32 s21, s21, 2
	s_add_u32 s54, s54, 0x100
	s_addc_u32 s55, s55, 0
	s_add_u32 s19, s19, 0x100
	s_addc_u32 s20, s20, 0
	s_cmp_gt_u32 s21, 13
	s_cbranch_scc0 .LBB0_673
	s_and_b64 vcc, exec, s[44:45]
	s_cbranch_vccz .LBB0_676
	s_barrier

.LBB0_738:
	s_waitcnt vmcnt(0) lgkmcnt(0)
	s_mov_b32 s79, 0x3e38aa3b
	s_mov_b32 s77, 0xc000
	s_mov_b32 s78, 0xffffc000
	v_readlane_b32 s1, v253, 23
	v_readfirstlane_b32 s0, v170
	s_nop 3
	s_lshr_b32 s0, s0, 6
	s_and_b32 s74, s1, 7
	s_lshl_b32 s74, s74, 5
	s_lshr_b32 s75, s1, 3
	s_add_u32 s74, s74, s75
	s_lshl_b32 s74, s74, 3
	s_and_b32 s4, s74, 31
	s_lshr_b32 s75, s74, 5
	s_and_b32 s5, s75, 0
	s_lshr_b32 s75, s75, 0
	s_and_b32 s3, s75, 3
	s_lshr_b32 s2, s75, 2
	s_sub_u32 s6, 8, s0
	s_lshl_b32 s70, s0, 10
	s_lshl_b32 s74, s2, 21
	s_lshl_b32 s75, s3, 19
	s_add_u32 s74, s74, s75
	s_add_u32 s34, s40, s74
	s_addc_u32 s35, s41, 0
	s_mov_b32 s30, s34
	s_mov_b32 s31, s35
	s_lshl_b32 s74, s2, 16
	s_lshl_b32 s75, s3, 14
	s_add_u32 s74, s74, s75
	s_add_u32 s74, s74, 0xc000000
	s_add_u32 s58, s42, s74
	s_addc_u32 s59, s43, 0
	s_add_u32 s74, s2, 0
	s_lshl_b32 s74, s74, 2
	s_add_u32 s74, s74, s3
	s_lshl_b32 s74, s74, 19
	s_add_u32 s60, s42, s74
	s_addc_u32 s61, s43, 0
	s_lshl_b32 s74, s2, 6
	s_add_u32 s74, s74, 0
	s_lshl_b32 s74, s74, 15
	s_lshl_b32 s75, s3, 13
	s_add_u32 s74, s74, s75
	s_add_u32 s74, s74, 0x6000000
	s_add_u32 s64, s42, s74
	s_addc_u32 s65, s43, 0
	v_and_b32_e32 v141, 63, v170
	v_and_b32_e32 v241, 15, v141
	v_lshrrev_b32_e32 v242, 4, v141
	v_mov_b32_e32 v244, 0xf149f2ca
	v_mov_b32_e32 v248, 0
	v_mov_b32_e32 v249, 0
	v_lshrrev_b32_e32 v142, 1, v241
	v_xor_b32_e32 v142, v142, v242
	v_lshlrev_b32_e32 v142, 4, v142
	v_lshl_add_u32 v142, v241, 7, v142
	s_lshl_b32 s74, s0, 11
	v_add_u32_e32 v230, s74, v142
	v_xor_b32_e32 v231, 64, v230
	v_lshrrev_b32_e32 v142, 1, v242
	v_xor_b32_e32 v243, v142, v241
	v_and_b32_e32 v142, 1, v242
	v_lshlrev_b32_e32 v142, 3, v142
	v_lshl_add_u32 v142, v241, 8, v142
	v_add_u32_e32 v142, 0x10000, v142
	s_add_u32 s74, s0, 0
	s_and_b32 s75, s74, 7
	s_lshl_b32 s75, s75, 1
	s_lshr_b32 s74, s74, 3
	s_lshl_b32 s74, s74, 14
	v_xor_b32_e32 v143, s75, v243
	v_lshl_add_u32 v143, v143, 4, v142
	v_add_u32_e32 v221, s74, v143
	s_add_u32 s74, s0, 1
	s_and_b32 s75, s74, 7
	s_lshl_b32 s75, s75, 1
	s_lshr_b32 s74, s74, 3
	s_lshl_b32 s74, s74, 14
	v_xor_b32_e32 v143, s75, v243
	v_lshl_add_u32 v143, v143, 4, v142
	v_add_u32_e32 v222, s74, v143
	s_add_u32 s74, s0, 2
	s_and_b32 s75, s74, 7
	s_lshl_b32 s75, s75, 1
	s_lshr_b32 s74, s74, 3
	s_lshl_b32 s74, s74, 14
	v_xor_b32_e32 v143, s75, v243
	v_lshl_add_u32 v143, v143, 4, v142
	v_add_u32_e32 v223, s74, v143
	s_add_u32 s74, s0, 3
	s_and_b32 s75, s74, 7
	s_lshl_b32 s75, s75, 1
	s_lshr_b32 s74, s74, 3
	s_lshl_b32 s74, s74, 14
	v_xor_b32_e32 v143, s75, v243
	v_lshl_add_u32 v143, v143, 4, v142
	v_add_u32_e32 v224, s74, v143
	s_add_u32 s74, s0, 4
	s_and_b32 s75, s74, 7
	s_lshl_b32 s75, s75, 1
	s_lshr_b32 s74, s74, 3
	s_lshl_b32 s74, s74, 14
	v_xor_b32_e32 v143, s75, v243
	v_lshl_add_u32 v143, v143, 4, v142
	v_add_u32_e32 v225, s74, v143
	s_add_u32 s74, s0, 5
	s_and_b32 s75, s74, 7
	s_lshl_b32 s75, s75, 1
	s_lshr_b32 s74, s74, 3
	s_lshl_b32 s74, s74, 14
	v_xor_b32_e32 v143, s75, v243
	v_lshl_add_u32 v143, v143, 4, v142
	v_add_u32_e32 v226, s74, v143
	s_add_u32 s74, s0, 6
	s_and_b32 s75, s74, 7
	s_lshl_b32 s75, s75, 1
	s_lshr_b32 s74, s74, 3
	s_lshl_b32 s74, s74, 14
	v_xor_b32_e32 v143, s75, v243
	v_lshl_add_u32 v143, v143, 4, v142
	v_add_u32_e32 v227, s74, v143
	s_add_u32 s74, s0, 7
	s_and_b32 s75, s74, 7
	s_lshl_b32 s75, s75, 1
	s_lshr_b32 s74, s74, 3
	s_lshl_b32 s74, s74, 14
	v_xor_b32_e32 v143, s75, v243
	v_lshl_add_u32 v143, v143, 4, v142
	v_add_u32_e32 v228, s74, v143
	s_add_u32 s74, s0, 8
	s_and_b32 s75, s74, 7
	s_lshl_b32 s75, s75, 1
	s_lshr_b32 s74, s74, 3
	s_lshl_b32 s74, s74, 14
	v_xor_b32_e32 v143, s75, v243
	v_lshl_add_u32 v143, v143, 4, v142
	v_add_u32_e32 v229, s74, v143
	s_and_b32 s74, s0, 1
	s_lshl_b32 s74, s74, 2
	v_add_u32_e32 v142, s74, v242
	v_and_b32_e32 v143, 7, v141
	v_xor_b32_e32 v142, v142, v143
	v_lshlrev_b32_e32 v142, 4, v142
	v_lshrrev_b32_e32 v143, 3, v141
	s_lshl_b32 s74, s0, 3
	v_add_u32_e32 v143, s74, v143
	v_lshl_add_u32 v232, v143, 7, v142
	v_add_u32_e32 v233, 0x2000, v232
	s_and_b32 s74, s0, 3
	s_lshl_b32 s74, s74, 2
	v_add_u32_e32 v142, s74, v242
	v_xor_b32_e32 v142, v142, v241
	v_lshlrev_b32_e32 v142, 4, v142
	s_lshl_b32 s74, s0, 2
	v_add_u32_e32 v143, s74, v242
	v_lshl_add_u32 v234, v143, 15, v142
	v_add_u32_e32 v235, 0x100000, v234
	s_lshl_b32 s74, s0, 4
	v_add_u32_e32 v142, s74, v241
	v_lshlrev_b32_e32 v142, 0, v142
	v_lshlrev_b32_e32 v238, 2, v142
	v_lshlrev_b32_e32 v142, 7, v142
	v_lshl_add_u32 v236, v242, 4, v142
	v_lshl_add_u32 v237, v242, 3, v142
	v_xor_b32_e32 v142, 16, v141
	v_lshlrev_b32_e32 v239, 2, v142
	v_xor_b32_e32 v142, 32, v141
	v_lshlrev_b32_e32 v240, 2, v142
	s_add_u32 s74, s2, 1
	v_cvt_f32_u32_e32 v142, s74
	v_mul_f32_e32 v142, 0xc1000000, v142
	v_mul_f32_e32 v142, 0x3caaaaab, v142
	v_exp_f32_e32 v142, v142
	v_lshlrev_b32_e32 v144, 2, v242
	v_sub_u32_e32 v145, v241, v144
	v_mul_f32_e32 v142, 0x3f800000, v142
	v_add_u32_e32 v145, 0x80, v145
	v_mul_f32_e32 v142, 0x3fb8aa3b, v142
	v_cvt_f32_i32_e32 v145, v145
	s_nop 0
	v_mul_f32_e64 v143, -v142, v145
	v_fmamk_f32 v185, v142, 0x0, v143
	v_fmamk_f32 v186, v142, 0x3f800000, v143
	v_fmamk_f32 v187, v142, 0x40000000, v143
	v_fmamk_f32 v188, v142, 0x40400000, v143
	v_fmamk_f32 v189, v142, 0x41800000, v143
	v_fmamk_f32 v190, v142, 0x41880000, v143
	v_fmamk_f32 v191, v142, 0x41900000, v143
	v_fmamk_f32 v192, v142, 0x41980000, v143
	v_fmamk_f32 v193, v142, 0x42000000, v143
	v_fmamk_f32 v194, v142, 0x42040000, v143
	v_fmamk_f32 v195, v142, 0x42080000, v143
	v_fmamk_f32 v196, v142, 0x420c0000, v143
	v_fmamk_f32 v197, v142, 0x42400000, v143
	v_fmamk_f32 v198, v142, 0x42440000, v143
	v_fmamk_f32 v199, v142, 0x42480000, v143
	v_fmamk_f32 v200, v142, 0x424c0000, v143
	v_fmamk_f32 v201, v142, 0x42800000, v143
	v_fmamk_f32 v202, v142, 0x42820000, v143
	v_fmamk_f32 v203, v142, 0x42840000, v143
	v_fmamk_f32 v204, v142, 0x42860000, v143
	v_fmamk_f32 v205, v142, 0x42a00000, v143
	v_fmamk_f32 v206, v142, 0x42a20000, v143
	v_fmamk_f32 v207, v142, 0x42a40000, v143
	v_fmamk_f32 v208, v142, 0x42a60000, v143
	v_fmamk_f32 v209, v142, 0x42c00000, v143
	v_fmamk_f32 v210, v142, 0x42c20000, v143
	v_fmamk_f32 v211, v142, 0x42c40000, v143
	v_fmamk_f32 v212, v142, 0x42c60000, v143
	v_fmamk_f32 v213, v142, 0x42e00000, v143
	v_fmamk_f32 v214, v142, 0x42e20000, v143
	v_fmamk_f32 v215, v142, 0x42e40000, v143
	v_fmamk_f32 v216, v142, 0x42e60000, v143
	v_fmamk_f32 v217, v142, 0x43000000, v143
	v_fmamk_f32 v218, v142, 0x43010000, v143
	v_fmamk_f32 v219, v142, 0x43020000, v143
	v_fmamk_f32 v220, v142, 0x43030000, v143
	v_add_u32_e32 v145, 0, v144
	v_cmp_lt_u32_e32 vcc, v145, v241
	s_nop 1
	v_cndmask_b32_e32 v185, v185, v244, vcc
	v_cmp_gt_u32_e32 vcc, v145, v241
	s_nop 1
	v_cndmask_b32_e32 v217, v217, v244, vcc
	v_add_u32_e32 v145, 1, v144
	v_cmp_lt_u32_e32 vcc, v145, v241
	s_nop 1
	v_cndmask_b32_e32 v186, v186, v244, vcc
	v_cmp_gt_u32_e32 vcc, v145, v241
	s_nop 1
	v_cndmask_b32_e32 v218, v218, v244, vcc
	v_add_u32_e32 v145, 2, v144
	v_cmp_lt_u32_e32 vcc, v145, v241
	s_nop 1
	v_cndmask_b32_e32 v187, v187, v244, vcc
	v_cmp_gt_u32_e32 vcc, v145, v241
	s_nop 1
	v_cndmask_b32_e32 v219, v219, v244, vcc
	v_add_u32_e32 v145, 3, v144
	v_cmp_lt_u32_e32 vcc, v145, v241
	s_nop 1
	v_cndmask_b32_e32 v188, v188, v244, vcc
	v_cmp_gt_u32_e32 vcc, v145, v241
	s_nop 1
	v_cndmask_b32_e32 v220, v220, v244, vcc
	s_lshl_b32 s74, s4, 7
	s_add_u32 s74, s74, s5
	s_lshl_b32 s75, s74, 7
	s_add_u32 s10, s30, s75
	s_addc_u32 s11, s31, 0
	s_add_u32 s86, s34, s75
	s_addc_u32 s87, s35, 0
	s_lshl_b32 s75, s74, 2
	s_add_u32 s88, s58, s75
	s_addc_u32 s89, s59, 0
	global_load_dwordx4 v[96:99], v236, s[10:11]
	global_load_dwordx4 v[100:103], v236, s[10:11] offset:64
	s_mov_b32 s7, 0
	s_nop 0
	s_nop 0

.LBB0_929:
	v_add_u32_e32 v149, s67, v147
	ds_read_b128 v[150:153], v149
	ds_read_b128 v[186:189], v149 offset:1024
	ds_read_b128 v[190:193], v149 offset:2048
	ds_read_b128 v[194:197], v149 offset:3072
	v_add_u32_e32 v149, s68, v147
	ds_read_b128 v[198:201], v149
	ds_read_b128 v[202:205], v149 offset:1024
	ds_read_b128 v[206:209], v149 offset:2048
	ds_read_b128 v[210:213], v149 offset:3072
	s_add_u32 s25, s54, 0xfffc0080
	s_addc_u32 s26, s55, -1
	s_cmp_eq_u32 s24, 12
	s_cselect_b32 s57, s17, s26
	s_cselect_b32 s56, s18, s25
	s_cselect_b32 s27, s19, s23
	s_cselect_b32 s26, s20, s21
	s_add_i32 m0, s3, 0xc000
	ds_read_b128 v[214:217], v148
	ds_read_b128 v[218:221], v148 offset:1024
	ds_read_b128 v[222:225], v148 offset:2048
	ds_read_b128 v[226:229], v148 offset:3072
	ds_read_b128 v[230:233], v148 offset:4096
	ds_read_b128 v[234:237], v148 offset:5120
	ds_read_b128 v[238:241], v148 offset:6144
	ds_read_b128 v[242:245], v148 offset:7168
	global_load_lds_dwordx4 v142, s[54:55]
	s_add_i32 m0, s3, 0xe000
	s_nop 0
	global_load_lds_dwordx4 v144, s[54:55]
	s_waitcnt vmcnt(8)
	s_waitcnt lgkmcnt(0)
	v_mfma_f32_16x16x32_f16 v[128:131], v[150:153], v[214:217], v[128:131]
	v_mfma_f32_16x16x32_f16 v[124:127], v[190:193], v[214:217], v[124:127]
	v_mfma_f32_16x16x32_f16 v[116:119], v[150:153], v[222:225], v[116:119]
	v_mfma_f32_16x16x32_f16 v[108:111], v[190:193], v[222:225], v[108:111]
	s_barrier
	s_setprio 1
	s_waitcnt lgkmcnt(0)
	v_mfma_f32_16x16x32_f16 v[104:107], v[150:153], v[230:233], v[104:107]
	v_mfma_f32_16x16x32_f16 v[100:103], v[190:193], v[230:233], v[100:103]
	v_mfma_f32_16x16x32_f16 v[88:91], v[150:153], v[238:241], v[88:91]
	v_mfma_f32_16x16x32_f16 v[84:87], v[190:193], v[238:241], v[84:87]
	v_mfma_f32_16x16x32_f16 v[128:131], v[186:189], v[218:221], v[128:131]
	v_mfma_f32_16x16x32_f16 v[124:127], v[194:197], v[218:221], v[124:127]
	v_mfma_f32_16x16x32_f16 v[116:119], v[186:189], v[226:229], v[116:119]
	v_mfma_f32_16x16x32_f16 v[108:111], v[194:197], v[226:229], v[108:111]
	v_mfma_f32_16x16x32_f16 v[104:107], v[186:189], v[234:237], v[104:107]
	v_mfma_f32_16x16x32_f16 v[100:103], v[194:197], v[234:237], v[100:103]
	v_mfma_f32_16x16x32_f16 v[88:91], v[186:189], v[242:245], v[88:91]
	v_mfma_f32_16x16x32_f16 v[84:87], v[194:197], v[242:245], v[84:87]
	s_setprio 0
	s_setprio 1
	v_mfma_f32_16x16x32_f16 v[120:123], v[198:201], v[214:217], v[120:123]
	v_mfma_f32_16x16x32_f16 v[112:115], v[206:209], v[214:217], v[112:115]
	v_mfma_f32_16x16x32_f16 v[96:99], v[198:201], v[222:225], v[96:99]
	v_mfma_f32_16x16x32_f16 v[92:95], v[206:209], v[222:225], v[92:95]
	v_mfma_f32_16x16x32_f16 v[80:83], v[198:201], v[230:233], v[80:83]
	v_mfma_f32_16x16x32_f16 v[76:79], v[206:209], v[230:233], v[76:79]
	v_mfma_f32_16x16x32_f16 v[72:75], v[198:201], v[238:241], v[72:75]
	v_mfma_f32_16x16x32_f16 v[68:71], v[206:209], v[238:241], v[68:71]
	v_mfma_f32_16x16x32_f16 v[120:123], v[202:205], v[218:221], v[120:123]
	v_mfma_f32_16x16x32_f16 v[112:115], v[210:213], v[218:221], v[112:115]
	v_mfma_f32_16x16x32_f16 v[96:99], v[202:205], v[226:229], v[96:99]
	v_mfma_f32_16x16x32_f16 v[92:95], v[210:213], v[226:229], v[92:95]
	v_mfma_f32_16x16x32_f16 v[80:83], v[202:205], v[234:237], v[80:83]
	v_mfma_f32_16x16x32_f16 v[76:79], v[210:213], v[234:237], v[76:79]
	v_mfma_f32_16x16x32_f16 v[72:75], v[202:205], v[242:245], v[72:75]
	v_mfma_f32_16x16x32_f16 v[68:71], v[210:213], v[242:245], v[68:71]
	s_setprio 0
	s_barrier
	s_add_i32 s25, s67, s2
	s_mov_b32 m0, s25
	ds_read_b128 v[214:217], v148 offset:16384
	ds_read_b128 v[218:221], v148 offset:17408
	ds_read_b128 v[222:225], v148 offset:18432
	ds_read_b128 v[226:229], v148 offset:19456
	ds_read_b128 v[230:233], v148 offset:20480
	ds_read_b128 v[234:237], v148 offset:21504
	ds_read_b128 v[238:241], v148 offset:22528
	ds_read_b128 v[242:245], v148 offset:23552
	global_load_lds_dwordx4 v136, s[26:27]
	s_add_i32 m0, s25, 0x2000
	s_add_i32 s25, s68, s2
	global_load_lds_dwordx4 v0, s[26:27]
	s_mov_b32 m0, s25
	s_nop 0
	global_load_lds_dwordx4 v138, s[26:27]
	s_add_i32 m0, s25, 0x2000
	s_nop 0
	global_load_lds_dwordx4 v132, s[26:27]
	s_mov_b32 m0, s3
	s_nop 0
	global_load_lds_dwordx4 v140, s[56:57]
	s_mov_b32 m0, s8
	s_nop 0
	global_load_lds_dwordx4 v134, s[56:57]
	s_waitcnt vmcnt(8)
	s_waitcnt lgkmcnt(0)
	v_mfma_f32_16x16x32_f16 v[64:67], v[150:153], v[214:217], v[64:67]
	v_mfma_f32_16x16x32_f16 v[60:63], v[190:193], v[214:217], v[60:63]
	v_mfma_f32_16x16x32_f16 v[56:59], v[150:153], v[222:225], v[56:59]
	v_mfma_f32_16x16x32_f16 v[52:55], v[190:193], v[222:225], v[52:55]
	s_barrier
	s_setprio 1
	s_waitcnt lgkmcnt(0)
	v_mfma_f32_16x16x32_f16 v[40:43], v[150:153], v[230:233], v[40:43]
	v_mfma_f32_16x16x32_f16 v[36:39], v[190:193], v[230:233], v[36:39]
	v_mfma_f32_16x16x32_f16 v[24:27], v[150:153], v[238:241], v[24:27]
	v_mfma_f32_16x16x32_f16 v[20:23], v[190:193], v[238:241], v[20:23]
	v_mfma_f32_16x16x32_f16 v[64:67], v[186:189], v[218:221], v[64:67]
	v_mfma_f32_16x16x32_f16 v[60:63], v[194:197], v[218:221], v[60:63]
	v_mfma_f32_16x16x32_f16 v[56:59], v[186:189], v[226:229], v[56:59]
	v_mfma_f32_16x16x32_f16 v[52:55], v[194:197], v[226:229], v[52:55]
	v_mfma_f32_16x16x32_f16 v[40:43], v[186:189], v[234:237], v[40:43]
	v_mfma_f32_16x16x32_f16 v[36:39], v[194:197], v[234:237], v[36:39]
	v_mfma_f32_16x16x32_f16 v[24:27], v[186:189], v[242:245], v[24:27]
	v_mfma_f32_16x16x32_f16 v[20:23], v[194:197], v[242:245], v[20:23]
	s_setprio 0
	s_setprio 1
	v_mfma_f32_16x16x32_f16 v[48:51], v[198:201], v[214:217], v[48:51]
	v_mfma_f32_16x16x32_f16 v[44:47], v[206:209], v[214:217], v[44:47]
	v_mfma_f32_16x16x32_f16 v[32:35], v[198:201], v[222:225], v[32:35]
	v_mfma_f32_16x16x32_f16 v[28:31], v[206:209], v[222:225], v[28:31]
	v_mfma_f32_16x16x32_f16 v[16:19], v[198:201], v[230:233], v[16:19]
	v_mfma_f32_16x16x32_f16 v[12:15], v[206:209], v[230:233], v[12:15]
	v_mfma_f32_16x16x32_f16 v[8:11], v[198:201], v[238:241], v[8:11]
	v_mfma_f32_16x16x32_f16 v[4:7], v[206:209], v[238:241], v[4:7]
	v_mfma_f32_16x16x32_f16 v[48:51], v[202:205], v[218:221], v[48:51]
	v_mfma_f32_16x16x32_f16 v[44:47], v[210:213], v[218:221], v[44:47]
	v_mfma_f32_16x16x32_f16 v[32:35], v[202:205], v[226:229], v[32:35]
	v_mfma_f32_16x16x32_f16 v[28:31], v[210:213], v[226:229], v[28:31]
	v_mfma_f32_16x16x32_f16 v[16:19], v[202:205], v[234:237], v[16:19]
	v_mfma_f32_16x16x32_f16 v[12:15], v[210:213], v[234:237], v[12:15]
	v_mfma_f32_16x16x32_f16 v[8:11], v[202:205], v[242:245], v[8:11]
	v_mfma_f32_16x16x32_f16 v[4:7], v[210:213], v[242:245], v[4:7]
	s_setprio 0
	s_barrier
	v_add_u32_e32 v149, s82, v147
	ds_read_b128 v[150:153], v149
	ds_read_b128 v[186:189], v149 offset:1024
	ds_read_b128 v[190:193], v149 offset:2048
	ds_read_b128 v[194:197], v149 offset:3072
	v_add_u32_e32 v149, s62, v147
	ds_read_b128 v[198:201], v149
	ds_read_b128 v[202:205], v149 offset:1024
	ds_read_b128 v[206:209], v149 offset:2048
	ds_read_b128 v[210:213], v149 offset:3072
	s_add_u32 s56, s56, 0x40000
	s_addc_u32 s57, s57, 0
	s_mov_b32 m0, s9
	ds_read_b128 v[214:217], v148 offset:32768
	ds_read_b128 v[218:221], v148 offset:33792
	ds_read_b128 v[222:225], v148 offset:34816
	ds_read_b128 v[226:229], v148 offset:35840
	ds_read_b128 v[230:233], v148 offset:36864
	ds_read_b128 v[234:237], v148 offset:37888
	ds_read_b128 v[238:241], v148 offset:38912
	ds_read_b128 v[242:245], v148 offset:39936
	global_load_lds_dwordx4 v140, s[56:57]
	s_mov_b32 m0, s10
	s_nop 0
	global_load_lds_dwordx4 v134, s[56:57]
	s_waitcnt vmcnt(8)
	s_waitcnt lgkmcnt(0)
	v_mfma_f32_16x16x32_f16 v[128:131], v[150:153], v[214:217], v[128:131]
	v_mfma_f32_16x16x32_f16 v[124:127], v[190:193], v[214:217], v[124:127]
	v_mfma_f32_16x16x32_f16 v[116:119], v[150:153], v[222:225], v[116:119]
	v_mfma_f32_16x16x32_f16 v[108:111], v[190:193], v[222:225], v[108:111]
	s_barrier
	s_setprio 1
	s_waitcnt lgkmcnt(0)
	v_mfma_f32_16x16x32_f16 v[104:107], v[150:153], v[230:233], v[104:107]
	v_mfma_f32_16x16x32_f16 v[100:103], v[190:193], v[230:233], v[100:103]
	v_mfma_f32_16x16x32_f16 v[88:91], v[150:153], v[238:241], v[88:91]
	v_mfma_f32_16x16x32_f16 v[84:87], v[190:193], v[238:241], v[84:87]
	v_mfma_f32_16x16x32_f16 v[128:131], v[186:189], v[218:221], v[128:131]
	v_mfma_f32_16x16x32_f16 v[124:127], v[194:197], v[218:221], v[124:127]
	v_mfma_f32_16x16x32_f16 v[116:119], v[186:189], v[226:229], v[116:119]
	v_mfma_f32_16x16x32_f16 v[108:111], v[194:197], v[226:229], v[108:111]
	v_mfma_f32_16x16x32_f16 v[104:107], v[186:189], v[234:237], v[104:107]
	v_mfma_f32_16x16x32_f16 v[100:103], v[194:197], v[234:237], v[100:103]
	v_mfma_f32_16x16x32_f16 v[88:91], v[186:189], v[242:245], v[88:91]
	v_mfma_f32_16x16x32_f16 v[84:87], v[194:197], v[242:245], v[84:87]
	s_setprio 0
	s_setprio 1
	v_mfma_f32_16x16x32_f16 v[120:123], v[198:201], v[214:217], v[120:123]
	v_mfma_f32_16x16x32_f16 v[112:115], v[206:209], v[214:217], v[112:115]
	v_mfma_f32_16x16x32_f16 v[96:99], v[198:201], v[222:225], v[96:99]
	v_mfma_f32_16x16x32_f16 v[92:95], v[206:209], v[222:225], v[92:95]
	v_mfma_f32_16x16x32_f16 v[80:83], v[198:201], v[230:233], v[80:83]
	v_mfma_f32_16x16x32_f16 v[76:79], v[206:209], v[230:233], v[76:79]
	v_mfma_f32_16x16x32_f16 v[72:75], v[198:201], v[238:241], v[72:75]
	v_mfma_f32_16x16x32_f16 v[68:71], v[206:209], v[238:241], v[68:71]
	v_mfma_f32_16x16x32_f16 v[120:123], v[202:205], v[218:221], v[120:123]
	v_mfma_f32_16x16x32_f16 v[112:115], v[210:213], v[218:221], v[112:115]
	v_mfma_f32_16x16x32_f16 v[96:99], v[202:205], v[226:229], v[96:99]
	v_mfma_f32_16x16x32_f16 v[92:95], v[210:213], v[226:229], v[92:95]
	v_mfma_f32_16x16x32_f16 v[80:83], v[202:205], v[234:237], v[80:83]
	v_mfma_f32_16x16x32_f16 v[76:79], v[210:213], v[234:237], v[76:79]
	v_mfma_f32_16x16x32_f16 v[72:75], v[202:205], v[242:245], v[72:75]
	v_mfma_f32_16x16x32_f16 v[68:71], v[210:213], v[242:245], v[68:71]
	s_setprio 0
	s_barrier
	s_add_i32 s25, s82, s2
	s_add_u32 s26, s26, 0x80
	s_addc_u32 s27, s27, 0
	s_add_u32 s56, s56, 0xfffc0080
	s_addc_u32 s57, s57, -1
	s_mov_b32 m0, s25
	ds_read_b128 v[214:217], v148 offset:49152
	ds_read_b128 v[218:221], v148 offset:50176
	ds_read_b128 v[222:225], v148 offset:51200
	ds_read_b128 v[226:229], v148 offset:52224
	ds_read_b128 v[230:233], v148 offset:53248
	ds_read_b128 v[234:237], v148 offset:54272
	ds_read_b128 v[238:241], v148 offset:55296
	ds_read_b128 v[242:245], v148 offset:56320
	global_load_lds_dwordx4 v136, s[26:27]
	s_add_i32 m0, s25, 0x2000
	s_add_i32 s25, s62, s2
	global_load_lds_dwordx4 v0, s[26:27]
	s_mov_b32 m0, s25
	s_nop 0
	global_load_lds_dwordx4 v138, s[26:27]
	s_add_i32 m0, s25, 0x2000
	s_nop 0
	global_load_lds_dwordx4 v132, s[26:27]
	s_mov_b32 m0, s12
	s_nop 0
	global_load_lds_dwordx4 v140, s[56:57]
	s_mov_b32 m0, s13
	s_nop 0
	global_load_lds_dwordx4 v134, s[56:57]
	s_waitcnt vmcnt(8)
	s_waitcnt lgkmcnt(0)
	v_mfma_f32_16x16x32_f16 v[64:67], v[150:153], v[214:217], v[64:67]
	v_mfma_f32_16x16x32_f16 v[60:63], v[190:193], v[214:217], v[60:63]
	v_mfma_f32_16x16x32_f16 v[56:59], v[150:153], v[222:225], v[56:59]
	v_mfma_f32_16x16x32_f16 v[52:55], v[190:193], v[222:225], v[52:55]
	s_barrier
	s_setprio 1
	s_waitcnt lgkmcnt(0)
	v_mfma_f32_16x16x32_f16 v[40:43], v[150:153], v[230:233], v[40:43]
	v_mfma_f32_16x16x32_f16 v[36:39], v[190:193], v[230:233], v[36:39]
	v_mfma_f32_16x16x32_f16 v[24:27], v[150:153], v[238:241], v[24:27]
	v_mfma_f32_16x16x32_f16 v[20:23], v[190:193], v[238:241], v[20:23]
	v_mfma_f32_16x16x32_f16 v[64:67], v[186:189], v[218:221], v[64:67]
	v_mfma_f32_16x16x32_f16 v[60:63], v[194:197], v[218:221], v[60:63]
	v_mfma_f32_16x16x32_f16 v[56:59], v[186:189], v[226:229], v[56:59]
	v_mfma_f32_16x16x32_f16 v[52:55], v[194:197], v[226:229], v[52:55]
	v_mfma_f32_16x16x32_f16 v[40:43], v[186:189], v[234:237], v[40:43]
	v_mfma_f32_16x16x32_f16 v[36:39], v[194:197], v[234:237], v[36:39]
	v_mfma_f32_16x16x32_f16 v[24:27], v[186:189], v[242:245], v[24:27]
	v_mfma_f32_16x16x32_f16 v[20:23], v[194:197], v[242:245], v[20:23]
	s_setprio 0
	s_setprio 1
	v_mfma_f32_16x16x32_f16 v[48:51], v[198:201], v[214:217], v[48:51]
	v_mfma_f32_16x16x32_f16 v[44:47], v[206:209], v[214:217], v[44:47]
	v_mfma_f32_16x16x32_f16 v[32:35], v[198:201], v[222:225], v[32:35]
	v_mfma_f32_16x16x32_f16 v[28:31], v[206:209], v[222:225], v[28:31]
	v_mfma_f32_16x16x32_f16 v[16:19], v[198:201], v[230:233], v[16:19]
	v_mfma_f32_16x16x32_f16 v[12:15], v[206:209], v[230:233], v[12:15]
	v_mfma_f32_16x16x32_f16 v[8:11], v[198:201], v[238:241], v[8:11]
	v_mfma_f32_16x16x32_f16 v[4:7], v[206:209], v[238:241], v[4:7]
	v_mfma_f32_16x16x32_f16 v[48:51], v[202:205], v[218:221], v[48:51]
	v_mfma_f32_16x16x32_f16 v[44:47], v[210:213], v[218:221], v[44:47]
	v_mfma_f32_16x16x32_f16 v[32:35], v[202:205], v[226:229], v[32:35]
	v_mfma_f32_16x16x32_f16 v[28:31], v[210:213], v[226:229], v[28:31]
	v_mfma_f32_16x16x32_f16 v[16:19], v[202:205], v[234:237], v[16:19]
	v_mfma_f32_16x16x32_f16 v[12:15], v[210:213], v[234:237], v[12:15]
	v_mfma_f32_16x16x32_f16 v[8:11], v[202:205], v[242:245], v[8:11]
	v_mfma_f32_16x16x32_f16 v[4:7], v[210:213], v[242:245], v[4:7]
	s_setprio 0
	s_barrier
	s_add_i32 s24, s24, 2
	s_add_u32 s54, s54, 0x100
	s_addc_u32 s55, s55, 0
	s_add_u32 s21, s21, 0x100
	s_addc_u32 s23, s23, 0
	s_cmp_gt_u32 s24, 13
	s_cbranch_scc0 .LBB0_929
	s_and_b64 vcc, exec, s[44:45]
	s_cbranch_vccz .LBB0_932
	s_barrier

.LBB0_991:
	s_waitcnt vmcnt(0) lgkmcnt(0)
	s_mov_b32 s79, 0x3e38aa3b
	s_mov_b32 s77, 0xc000
	s_mov_b32 s78, 0xffffc000
	v_readlane_b32 s1, v253, 23
	v_readfirstlane_b32 s0, v170
	s_nop 3
	s_lshr_b32 s0, s0, 6
	s_and_b32 s74, s1, 7
	s_lshl_b32 s74, s74, 5
	s_lshr_b32 s75, s1, 3
	s_add_u32 s74, s74, s75
	s_lshl_b32 s74, s74, 3
	s_and_b32 s4, s74, 1
	s_lshr_b32 s75, s74, 1
	s_and_b32 s5, s75, 15
	s_lshr_b32 s75, s75, 4
	s_and_b32 s3, s75, 3
	s_lshr_b32 s2, s75, 2
	s_sub_u32 s6, 8, s0
	s_lshl_b32 s70, s0, 10
	s_lshl_b32 s74, s2, 21
	s_lshl_b32 s75, s3, 19
	s_add_u32 s74, s74, s75
	s_add_u32 s34, s40, s74
	s_addc_u32 s35, s41, 0
	s_add_u32 s30, s34, 0x2000000
	s_addc_u32 s31, s35, 0
	s_lshl_b32 s74, s2, 16
	s_lshl_b32 s75, s3, 14
	s_add_u32 s74, s74, s75
	s_add_u32 s74, s74, 0xc000000
	s_add_u32 s58, s42, s74
	s_addc_u32 s59, s43, 0
	s_add_u32 s74, s2, 32
	s_lshl_b32 s74, s74, 2
	s_add_u32 s74, s74, s3
	s_lshl_b32 s74, s74, 19
	s_add_u32 s60, s42, s74
	s_addc_u32 s61, s43, 0
	s_lshl_b32 s74, s2, 6
	s_add_u32 s74, s74, 2048
	s_lshl_b32 s74, s74, 15
	s_lshl_b32 s75, s3, 13
	s_add_u32 s74, s74, s75
	s_add_u32 s74, s74, 0x6000000
	s_add_u32 s64, s42, s74
	s_addc_u32 s65, s43, 0
	v_and_b32_e32 v141, 63, v170
	v_and_b32_e32 v241, 15, v141
	v_lshrrev_b32_e32 v242, 4, v141
	v_mov_b32_e32 v244, 0xf149f2ca
	v_mov_b32_e32 v248, 0
	v_mov_b32_e32 v249, 0
	v_lshrrev_b32_e32 v142, 1, v241
	v_xor_b32_e32 v142, v142, v242
	v_lshlrev_b32_e32 v142, 4, v142
	v_lshl_add_u32 v142, v241, 7, v142
	s_lshl_b32 s74, s0, 11
	v_add_u32_e32 v230, s74, v142
	v_xor_b32_e32 v231, 64, v230
	v_lshrrev_b32_e32 v142, 1, v242
	v_xor_b32_e32 v243, v142, v241
	v_and_b32_e32 v142, 1, v242
	v_lshlrev_b32_e32 v142, 3, v142
	v_lshl_add_u32 v142, v241, 8, v142
	v_add_u32_e32 v142, 0x10000, v142
	s_add_u32 s74, s0, 0
	s_and_b32 s75, s74, 7
	s_lshl_b32 s75, s75, 1
	s_lshr_b32 s74, s74, 3
	s_lshl_b32 s74, s74, 14
	v_xor_b32_e32 v143, s75, v243
	v_lshl_add_u32 v143, v143, 4, v142
	v_add_u32_e32 v221, s74, v143
	s_add_u32 s74, s0, 1
	s_and_b32 s75, s74, 7
	s_lshl_b32 s75, s75, 1
	s_lshr_b32 s74, s74, 3
	s_lshl_b32 s74, s74, 14
	v_xor_b32_e32 v143, s75, v243
	v_lshl_add_u32 v143, v143, 4, v142
	v_add_u32_e32 v222, s74, v143
	s_add_u32 s74, s0, 2
	s_and_b32 s75, s74, 7
	s_lshl_b32 s75, s75, 1
	s_lshr_b32 s74, s74, 3
	s_lshl_b32 s74, s74, 14
	v_xor_b32_e32 v143, s75, v243
	v_lshl_add_u32 v143, v143, 4, v142
	v_add_u32_e32 v223, s74, v143
	s_add_u32 s74, s0, 3
	s_and_b32 s75, s74, 7
	s_lshl_b32 s75, s75, 1
	s_lshr_b32 s74, s74, 3
	s_lshl_b32 s74, s74, 14
	v_xor_b32_e32 v143, s75, v243
	v_lshl_add_u32 v143, v143, 4, v142
	v_add_u32_e32 v224, s74, v143
	s_add_u32 s74, s0, 4
	s_and_b32 s75, s74, 7
	s_lshl_b32 s75, s75, 1
	s_lshr_b32 s74, s74, 3
	s_lshl_b32 s74, s74, 14
	v_xor_b32_e32 v143, s75, v243
	v_lshl_add_u32 v143, v143, 4, v142
	v_add_u32_e32 v225, s74, v143
	s_add_u32 s74, s0, 5
	s_and_b32 s75, s74, 7
	s_lshl_b32 s75, s75, 1
	s_lshr_b32 s74, s74, 3
	s_lshl_b32 s74, s74, 14
	v_xor_b32_e32 v143, s75, v243
	v_lshl_add_u32 v143, v143, 4, v142
	v_add_u32_e32 v226, s74, v143
	s_add_u32 s74, s0, 6
	s_and_b32 s75, s74, 7
	s_lshl_b32 s75, s75, 1
	s_lshr_b32 s74, s74, 3
	s_lshl_b32 s74, s74, 14
	v_xor_b32_e32 v143, s75, v243
	v_lshl_add_u32 v143, v143, 4, v142
	v_add_u32_e32 v227, s74, v143
	s_add_u32 s74, s0, 7
	s_and_b32 s75, s74, 7
	s_lshl_b32 s75, s75, 1
	s_lshr_b32 s74, s74, 3
	s_lshl_b32 s74, s74, 14
	v_xor_b32_e32 v143, s75, v243
	v_lshl_add_u32 v143, v143, 4, v142
	v_add_u32_e32 v228, s74, v143
	s_add_u32 s74, s0, 8
	s_and_b32 s75, s74, 7
	s_lshl_b32 s75, s75, 1
	s_lshr_b32 s74, s74, 3
	s_lshl_b32 s74, s74, 14
	v_xor_b32_e32 v143, s75, v243
	v_lshl_add_u32 v143, v143, 4, v142
	v_add_u32_e32 v229, s74, v143
	s_and_b32 s74, s0, 1
	s_lshl_b32 s74, s74, 2
	v_add_u32_e32 v142, s74, v242
	v_and_b32_e32 v143, 7, v141
	v_xor_b32_e32 v142, v142, v143
	v_lshlrev_b32_e32 v142, 4, v142
	v_lshrrev_b32_e32 v143, 3, v141
	s_lshl_b32 s74, s0, 3
	v_add_u32_e32 v143, s74, v143
	v_lshl_add_u32 v232, v143, 7, v142
	v_add_u32_e32 v233, 0x2000, v232
	s_and_b32 s74, s0, 3
	s_lshl_b32 s74, s74, 2
	v_add_u32_e32 v142, s74, v242
	v_xor_b32_e32 v142, v142, v241
	v_lshlrev_b32_e32 v142, 4, v142
	s_lshl_b32 s74, s0, 2
	v_add_u32_e32 v143, s74, v242
	v_lshl_add_u32 v234, v143, 15, v142
	v_add_u32_e32 v235, 0x100000, v234
	s_lshl_b32 s74, s0, 4
	v_add_u32_e32 v142, s74, v241
	v_lshlrev_b32_e32 v142, 4, v142
	v_lshlrev_b32_e32 v238, 2, v142
	v_lshlrev_b32_e32 v142, 7, v142
	v_lshl_add_u32 v236, v242, 4, v142
	v_lshl_add_u32 v237, v242, 3, v142
	v_xor_b32_e32 v142, 16, v141
	v_lshlrev_b32_e32 v239, 2, v142
	v_xor_b32_e32 v142, 32, v141
	v_lshlrev_b32_e32 v240, 2, v142
	s_add_u32 s74, s2, 33
	v_cvt_f32_u32_e32 v142, s74
	v_mul_f32_e32 v142, 0xc1000000, v142
	v_mul_f32_e32 v142, 0x3caaaaab, v142
	v_exp_f32_e32 v142, v142
	v_lshlrev_b32_e32 v144, 2, v242
	v_sub_u32_e32 v145, v241, v144
	v_mul_f32_e32 v142, 0x41800000, v142
	v_add_u32_e32 v145, 0x80, v145
	v_mul_f32_e32 v142, 0x3fb8aa3b, v142
	v_cvt_f32_i32_e32 v145, v145
	s_nop 0
	v_mul_f32_e64 v143, -v142, v145
	v_fmamk_f32 v185, v142, 0x0, v143
	v_fmamk_f32 v186, v142, 0x3f800000, v143
	v_fmamk_f32 v187, v142, 0x40000000, v143
	v_fmamk_f32 v188, v142, 0x40400000, v143
	v_fmamk_f32 v189, v142, 0x41800000, v143
	v_fmamk_f32 v190, v142, 0x41880000, v143
	v_fmamk_f32 v191, v142, 0x41900000, v143
	v_fmamk_f32 v192, v142, 0x41980000, v143
	v_fmamk_f32 v193, v142, 0x42000000, v143
	v_fmamk_f32 v194, v142, 0x42040000, v143
	v_fmamk_f32 v195, v142, 0x42080000, v143
	v_fmamk_f32 v196, v142, 0x420c0000, v143
	v_fmamk_f32 v197, v142, 0x42400000, v143
	v_fmamk_f32 v198, v142, 0x42440000, v143
	v_fmamk_f32 v199, v142, 0x42480000, v143
	v_fmamk_f32 v200, v142, 0x424c0000, v143
	v_fmamk_f32 v201, v142, 0x42800000, v143
	v_fmamk_f32 v202, v142, 0x42820000, v143
	v_fmamk_f32 v203, v142, 0x42840000, v143
	v_fmamk_f32 v204, v142, 0x42860000, v143
	v_fmamk_f32 v205, v142, 0x42a00000, v143
	v_fmamk_f32 v206, v142, 0x42a20000, v143
	v_fmamk_f32 v207, v142, 0x42a40000, v143
	v_fmamk_f32 v208, v142, 0x42a60000, v143
	v_fmamk_f32 v209, v142, 0x42c00000, v143
	v_fmamk_f32 v210, v142, 0x42c20000, v143
	v_fmamk_f32 v211, v142, 0x42c40000, v143
	v_fmamk_f32 v212, v142, 0x42c60000, v143
	v_fmamk_f32 v213, v142, 0x42e00000, v143
	v_fmamk_f32 v214, v142, 0x42e20000, v143
	v_fmamk_f32 v215, v142, 0x42e40000, v143
	v_fmamk_f32 v216, v142, 0x42e60000, v143
	v_fmamk_f32 v217, v142, 0x43000000, v143
	v_fmamk_f32 v218, v142, 0x43010000, v143
	v_fmamk_f32 v219, v142, 0x43020000, v143
	v_fmamk_f32 v220, v142, 0x43030000, v143
	v_add_u32_e32 v145, 0, v144
	v_cmp_lt_u32_e32 vcc, v145, v241
	s_nop 1
	v_cndmask_b32_e32 v185, v185, v244, vcc
	v_cmp_gt_u32_e32 vcc, v145, v241
	s_nop 1
	v_cndmask_b32_e32 v217, v217, v244, vcc
	v_add_u32_e32 v145, 1, v144
	v_cmp_lt_u32_e32 vcc, v145, v241
	s_nop 1
	v_cndmask_b32_e32 v186, v186, v244, vcc
	v_cmp_gt_u32_e32 vcc, v145, v241
	s_nop 1
	v_cndmask_b32_e32 v218, v218, v244, vcc
	v_add_u32_e32 v145, 2, v144
	v_cmp_lt_u32_e32 vcc, v145, v241
	s_nop 1
	v_cndmask_b32_e32 v187, v187, v244, vcc
	v_cmp_gt_u32_e32 vcc, v145, v241
	s_nop 1
	v_cndmask_b32_e32 v219, v219, v244, vcc
	v_add_u32_e32 v145, 3, v144
	v_cmp_lt_u32_e32 vcc, v145, v241
	s_nop 1
	v_cndmask_b32_e32 v188, v188, v244, vcc
	v_cmp_gt_u32_e32 vcc, v145, v241
	s_nop 1
	v_cndmask_b32_e32 v220, v220, v244, vcc
	s_lshl_b32 s74, s4, 11
	s_add_u32 s74, s74, s5
	s_lshl_b32 s75, s74, 7
	s_add_u32 s10, s30, s75
	s_addc_u32 s11, s31, 0
	s_add_u32 s86, s34, s75
	s_addc_u32 s87, s35, 0
	s_lshl_b32 s75, s74, 2
	s_add_u32 s88, s58, s75
	s_addc_u32 s89, s59, 0
	global_load_dwordx4 v[96:99], v236, s[10:11]
	global_load_dwordx4 v[100:103], v236, s[10:11] offset:64
	global_load_dwordx2 v[112:113], v237, s[86:87]
	global_load_dwordx2 v[114:115], v237, s[86:87] offset:32
	global_load_dwordx2 v[116:117], v237, s[86:87] offset:64
	global_load_dwordx2 v[118:119], v237, s[86:87] offset:96
	global_load_dword v120, v238, s[88:89]
	s_mov_b32 s7, 0
	s_nop 0

.LBB0_1074:
	v_add_u32_e32 v2, s67, v186
	ds_read_b128 v[132:135], v2
	ds_read_b128 v[150:153], v2 offset:1024
	ds_read_b128 v[188:191], v2 offset:2048
	ds_read_b128 v[192:195], v2 offset:3072
	v_add_u32_e32 v2, s68, v186
	ds_read_b128 v[196:199], v2
	ds_read_b128 v[200:203], v2 offset:1024
	ds_read_b128 v[204:207], v2 offset:2048
	ds_read_b128 v[208:211], v2 offset:3072
	s_add_u32 s13, s54, 0xfffc0080
	s_addc_u32 s14, s55, -1
	s_cmp_eq_u32 s12, 12
	s_cselect_b32 s57, s2, s14
	s_cselect_b32 s56, s3, s13
	s_cselect_b32 s15, s8, s11
	s_cselect_b32 s14, s9, s10
	s_add_i32 m0, s60, 0xc000
	ds_read_b128 v[212:215], v187
	ds_read_b128 v[216:219], v187 offset:1024
	ds_read_b128 v[220:223], v187 offset:2048
	ds_read_b128 v[224:227], v187 offset:3072
	ds_read_b128 v[228:231], v187 offset:4096
	ds_read_b128 v[232:235], v187 offset:5120
	ds_read_b128 v[236:239], v187 offset:6144
	ds_read_b128 v[240:243], v187 offset:7168
	global_load_lds_dwordx4 v146, s[54:55]
	s_add_i32 m0, s60, 0xe000
	s_nop 0
	global_load_lds_dwordx4 v148, s[54:55]
	s_waitcnt vmcnt(8)
	s_waitcnt lgkmcnt(0)
	v_mfma_f32_16x16x32_f16 v[128:131], v[132:135], v[212:215], v[128:131]
	v_mfma_f32_16x16x32_f16 v[124:127], v[188:191], v[212:215], v[124:127]
	v_mfma_f32_16x16x32_f16 v[112:115], v[132:135], v[220:223], v[112:115]
	v_mfma_f32_16x16x32_f16 v[108:111], v[188:191], v[220:223], v[108:111]
	s_barrier
	s_setprio 1
	s_waitcnt lgkmcnt(0)
	v_mfma_f32_16x16x32_f16 v[96:99], v[132:135], v[228:231], v[96:99]
	v_mfma_f32_16x16x32_f16 v[92:95], v[188:191], v[228:231], v[92:95]
	v_mfma_f32_16x16x32_f16 v[80:83], v[132:135], v[236:239], v[80:83]
	v_mfma_f32_16x16x32_f16 v[76:79], v[188:191], v[236:239], v[76:79]
	v_mfma_f32_16x16x32_f16 v[128:131], v[150:153], v[216:219], v[128:131]
	v_mfma_f32_16x16x32_f16 v[124:127], v[192:195], v[216:219], v[124:127]
	v_mfma_f32_16x16x32_f16 v[112:115], v[150:153], v[224:227], v[112:115]
	v_mfma_f32_16x16x32_f16 v[108:111], v[192:195], v[224:227], v[108:111]
	v_mfma_f32_16x16x32_f16 v[96:99], v[150:153], v[232:235], v[96:99]
	v_mfma_f32_16x16x32_f16 v[92:95], v[192:195], v[232:235], v[92:95]
	v_mfma_f32_16x16x32_f16 v[80:83], v[150:153], v[240:243], v[80:83]
	v_mfma_f32_16x16x32_f16 v[76:79], v[192:195], v[240:243], v[76:79]
	s_setprio 0
	s_setprio 1
	v_mfma_f32_16x16x32_f16 v[120:123], v[196:199], v[212:215], v[120:123]
	v_mfma_f32_16x16x32_f16 v[116:119], v[204:207], v[212:215], v[116:119]
	v_mfma_f32_16x16x32_f16 v[104:107], v[196:199], v[220:223], v[104:107]
	v_mfma_f32_16x16x32_f16 v[100:103], v[204:207], v[220:223], v[100:103]
	v_mfma_f32_16x16x32_f16 v[88:91], v[196:199], v[228:231], v[88:91]
	v_mfma_f32_16x16x32_f16 v[84:87], v[204:207], v[228:231], v[84:87]
	v_mfma_f32_16x16x32_f16 v[72:75], v[196:199], v[236:239], v[72:75]
	v_mfma_f32_16x16x32_f16 v[68:71], v[204:207], v[236:239], v[68:71]
	v_mfma_f32_16x16x32_f16 v[120:123], v[200:203], v[216:219], v[120:123]
	v_mfma_f32_16x16x32_f16 v[116:119], v[208:211], v[216:219], v[116:119]
	v_mfma_f32_16x16x32_f16 v[104:107], v[200:203], v[224:227], v[104:107]
	v_mfma_f32_16x16x32_f16 v[100:103], v[208:211], v[224:227], v[100:103]
	v_mfma_f32_16x16x32_f16 v[88:91], v[200:203], v[232:235], v[88:91]
	v_mfma_f32_16x16x32_f16 v[84:87], v[208:211], v[232:235], v[84:87]
	v_mfma_f32_16x16x32_f16 v[72:75], v[200:203], v[240:243], v[72:75]
	v_mfma_f32_16x16x32_f16 v[68:71], v[208:211], v[240:243], v[68:71]
	s_setprio 0
	s_barrier
	s_add_i32 s13, s67, s59
	s_mov_b32 m0, s13
	ds_read_b128 v[212:215], v187 offset:16384
	ds_read_b128 v[216:219], v187 offset:17408
	ds_read_b128 v[220:223], v187 offset:18432
	ds_read_b128 v[224:227], v187 offset:19456
	ds_read_b128 v[228:231], v187 offset:20480
	ds_read_b128 v[232:235], v187 offset:21504
	ds_read_b128 v[236:239], v187 offset:22528
	ds_read_b128 v[240:243], v187 offset:23552
	global_load_lds_dwordx4 v140, s[14:15]
	s_add_i32 m0, s13, 0x2000
	s_add_i32 s13, s68, s59
	global_load_lds_dwordx4 v0, s[14:15]
	s_mov_b32 m0, s13
	s_nop 0
	global_load_lds_dwordx4 v142, s[14:15]
	s_add_i32 m0, s13, 0x2000
	s_nop 0
	global_load_lds_dwordx4 v136, s[14:15]
	s_mov_b32 m0, s60
	s_nop 0
	global_load_lds_dwordx4 v144, s[56:57]
	s_mov_b32 m0, s61
	s_nop 0
	global_load_lds_dwordx4 v138, s[56:57]
	s_waitcnt vmcnt(8)
	s_waitcnt lgkmcnt(0)
	v_mfma_f32_16x16x32_f16 v[64:67], v[132:135], v[212:215], v[64:67]
	v_mfma_f32_16x16x32_f16 v[60:63], v[188:191], v[212:215], v[60:63]
	v_mfma_f32_16x16x32_f16 v[48:51], v[132:135], v[220:223], v[48:51]
	v_mfma_f32_16x16x32_f16 v[44:47], v[188:191], v[220:223], v[44:47]
	s_barrier
	s_setprio 1
	s_waitcnt lgkmcnt(0)
	v_mfma_f32_16x16x32_f16 v[32:35], v[132:135], v[228:231], v[32:35]
	v_mfma_f32_16x16x32_f16 v[28:31], v[188:191], v[228:231], v[28:31]
	v_mfma_f32_16x16x32_f16 v[16:19], v[132:135], v[236:239], v[16:19]
	v_mfma_f32_16x16x32_f16 v[12:15], v[188:191], v[236:239], v[12:15]
	v_mfma_f32_16x16x32_f16 v[64:67], v[150:153], v[216:219], v[64:67]
	v_mfma_f32_16x16x32_f16 v[60:63], v[192:195], v[216:219], v[60:63]
	v_mfma_f32_16x16x32_f16 v[48:51], v[150:153], v[224:227], v[48:51]
	v_mfma_f32_16x16x32_f16 v[44:47], v[192:195], v[224:227], v[44:47]
	v_mfma_f32_16x16x32_f16 v[32:35], v[150:153], v[232:235], v[32:35]
	v_mfma_f32_16x16x32_f16 v[28:31], v[192:195], v[232:235], v[28:31]
	v_mfma_f32_16x16x32_f16 v[16:19], v[150:153], v[240:243], v[16:19]
	v_mfma_f32_16x16x32_f16 v[12:15], v[192:195], v[240:243], v[12:15]
	s_setprio 0
	s_setprio 1
	v_mfma_f32_16x16x32_f16 v[56:59], v[196:199], v[212:215], v[56:59]
	v_mfma_f32_16x16x32_f16 v[52:55], v[204:207], v[212:215], v[52:55]
	v_mfma_f32_16x16x32_f16 v[40:43], v[196:199], v[220:223], v[40:43]
	v_mfma_f32_16x16x32_f16 v[36:39], v[204:207], v[220:223], v[36:39]
	v_mfma_f32_16x16x32_f16 v[24:27], v[196:199], v[228:231], v[24:27]
	v_mfma_f32_16x16x32_f16 v[20:23], v[204:207], v[228:231], v[20:23]
	v_mfma_f32_16x16x32_f16 v[8:11], v[196:199], v[236:239], v[8:11]
	v_mfma_f32_16x16x32_f16 v[4:7], v[204:207], v[236:239], v[4:7]
	v_mfma_f32_16x16x32_f16 v[56:59], v[200:203], v[216:219], v[56:59]
	v_mfma_f32_16x16x32_f16 v[52:55], v[208:211], v[216:219], v[52:55]
	v_mfma_f32_16x16x32_f16 v[40:43], v[200:203], v[224:227], v[40:43]
	v_mfma_f32_16x16x32_f16 v[36:39], v[208:211], v[224:227], v[36:39]
	v_mfma_f32_16x16x32_f16 v[24:27], v[200:203], v[232:235], v[24:27]
	v_mfma_f32_16x16x32_f16 v[20:23], v[208:211], v[232:235], v[20:23]
	v_mfma_f32_16x16x32_f16 v[8:11], v[200:203], v[240:243], v[8:11]
	v_mfma_f32_16x16x32_f16 v[4:7], v[208:211], v[240:243], v[4:7]
	s_setprio 0
	s_barrier
	v_add_u32_e32 v2, s82, v186
	ds_read_b128 v[132:135], v2
	ds_read_b128 v[150:153], v2 offset:1024
	ds_read_b128 v[188:191], v2 offset:2048
	ds_read_b128 v[192:195], v2 offset:3072
	v_add_u32_e32 v2, s62, v186
	ds_read_b128 v[196:199], v2
	ds_read_b128 v[200:203], v2 offset:1024
	ds_read_b128 v[204:207], v2 offset:2048
	ds_read_b128 v[208:211], v2 offset:3072
	s_add_u32 s56, s56, 0x40000
	s_addc_u32 s57, s57, 0
	s_mov_b32 m0, s90
	ds_read_b128 v[212:215], v187 offset:32768
	ds_read_b128 v[216:219], v187 offset:33792
	ds_read_b128 v[220:223], v187 offset:34816
	ds_read_b128 v[224:227], v187 offset:35840
	ds_read_b128 v[228:231], v187 offset:36864
	ds_read_b128 v[232:235], v187 offset:37888
	ds_read_b128 v[236:239], v187 offset:38912
	ds_read_b128 v[240:243], v187 offset:39936
	global_load_lds_dwordx4 v144, s[56:57]
	s_mov_b32 m0, s91
	s_nop 0
	global_load_lds_dwordx4 v138, s[56:57]
	s_waitcnt vmcnt(8)
	s_waitcnt lgkmcnt(0)
	v_mfma_f32_16x16x32_f16 v[128:131], v[132:135], v[212:215], v[128:131]
	v_mfma_f32_16x16x32_f16 v[124:127], v[188:191], v[212:215], v[124:127]
	v_mfma_f32_16x16x32_f16 v[112:115], v[132:135], v[220:223], v[112:115]
	v_mfma_f32_16x16x32_f16 v[108:111], v[188:191], v[220:223], v[108:111]
	s_barrier
	s_setprio 1
	s_waitcnt lgkmcnt(0)
	v_mfma_f32_16x16x32_f16 v[96:99], v[132:135], v[228:231], v[96:99]
	v_mfma_f32_16x16x32_f16 v[92:95], v[188:191], v[228:231], v[92:95]
	v_mfma_f32_16x16x32_f16 v[80:83], v[132:135], v[236:239], v[80:83]
	v_mfma_f32_16x16x32_f16 v[76:79], v[188:191], v[236:239], v[76:79]
	v_mfma_f32_16x16x32_f16 v[128:131], v[150:153], v[216:219], v[128:131]
	v_mfma_f32_16x16x32_f16 v[124:127], v[192:195], v[216:219], v[124:127]
	v_mfma_f32_16x16x32_f16 v[112:115], v[150:153], v[224:227], v[112:115]
	v_mfma_f32_16x16x32_f16 v[108:111], v[192:195], v[224:227], v[108:111]
	v_mfma_f32_16x16x32_f16 v[96:99], v[150:153], v[232:235], v[96:99]
	v_mfma_f32_16x16x32_f16 v[92:95], v[192:195], v[232:235], v[92:95]
	v_mfma_f32_16x16x32_f16 v[80:83], v[150:153], v[240:243], v[80:83]
	v_mfma_f32_16x16x32_f16 v[76:79], v[192:195], v[240:243], v[76:79]
	s_setprio 0
	s_setprio 1
	v_mfma_f32_16x16x32_f16 v[120:123], v[196:199], v[212:215], v[120:123]
	v_mfma_f32_16x16x32_f16 v[116:119], v[204:207], v[212:215], v[116:119]
	v_mfma_f32_16x16x32_f16 v[104:107], v[196:199], v[220:223], v[104:107]
	v_mfma_f32_16x16x32_f16 v[100:103], v[204:207], v[220:223], v[100:103]
	v_mfma_f32_16x16x32_f16 v[88:91], v[196:199], v[228:231], v[88:91]
	v_mfma_f32_16x16x32_f16 v[84:87], v[204:207], v[228:231], v[84:87]
	v_mfma_f32_16x16x32_f16 v[72:75], v[196:199], v[236:239], v[72:75]
	v_mfma_f32_16x16x32_f16 v[68:71], v[204:207], v[236:239], v[68:71]
	v_mfma_f32_16x16x32_f16 v[120:123], v[200:203], v[216:219], v[120:123]
	v_mfma_f32_16x16x32_f16 v[116:119], v[208:211], v[216:219], v[116:119]
	v_mfma_f32_16x16x32_f16 v[104:107], v[200:203], v[224:227], v[104:107]
	v_mfma_f32_16x16x32_f16 v[100:103], v[208:211], v[224:227], v[100:103]
	v_mfma_f32_16x16x32_f16 v[88:91], v[200:203], v[232:235], v[88:91]
	v_mfma_f32_16x16x32_f16 v[84:87], v[208:211], v[232:235], v[84:87]
	v_mfma_f32_16x16x32_f16 v[72:75], v[200:203], v[240:243], v[72:75]
	v_mfma_f32_16x16x32_f16 v[68:71], v[208:211], v[240:243], v[68:71]
	s_setprio 0
	s_barrier
	s_add_i32 s13, s82, s59
	s_add_u32 s14, s14, 0x80
	s_addc_u32 s15, s15, 0
	s_add_u32 s56, s56, 0xfffc0080
	s_addc_u32 s57, s57, -1
	s_mov_b32 m0, s13
	ds_read_b128 v[212:215], v187 offset:49152
	ds_read_b128 v[216:219], v187 offset:50176
	ds_read_b128 v[220:223], v187 offset:51200
	ds_read_b128 v[224:227], v187 offset:52224
	ds_read_b128 v[228:231], v187 offset:53248
	ds_read_b128 v[232:235], v187 offset:54272
	ds_read_b128 v[236:239], v187 offset:55296
	ds_read_b128 v[240:243], v187 offset:56320
	global_load_lds_dwordx4 v140, s[14:15]
	s_add_i32 m0, s13, 0x2000
	s_add_i32 s13, s62, s59
	global_load_lds_dwordx4 v0, s[14:15]
	s_mov_b32 m0, s13
	s_nop 0
	global_load_lds_dwordx4 v142, s[14:15]
	s_add_i32 m0, s13, 0x2000
	s_nop 0
	global_load_lds_dwordx4 v136, s[14:15]
	s_mov_b32 m0, s7
	s_nop 0
	global_load_lds_dwordx4 v144, s[56:57]
	s_mov_b32 m0, s86
	s_nop 0
	global_load_lds_dwordx4 v138, s[56:57]
	s_waitcnt vmcnt(8)
	s_waitcnt lgkmcnt(0)
	v_mfma_f32_16x16x32_f16 v[64:67], v[132:135], v[212:215], v[64:67]
	v_mfma_f32_16x16x32_f16 v[60:63], v[188:191], v[212:215], v[60:63]
	v_mfma_f32_16x16x32_f16 v[48:51], v[132:135], v[220:223], v[48:51]
	v_mfma_f32_16x16x32_f16 v[44:47], v[188:191], v[220:223], v[44:47]
	s_barrier
	s_setprio 1
	s_waitcnt lgkmcnt(0)
	v_mfma_f32_16x16x32_f16 v[32:35], v[132:135], v[228:231], v[32:35]
	v_mfma_f32_16x16x32_f16 v[28:31], v[188:191], v[228:231], v[28:31]
	v_mfma_f32_16x16x32_f16 v[16:19], v[132:135], v[236:239], v[16:19]
	v_mfma_f32_16x16x32_f16 v[12:15], v[188:191], v[236:239], v[12:15]
	v_mfma_f32_16x16x32_f16 v[64:67], v[150:153], v[216:219], v[64:67]
	v_mfma_f32_16x16x32_f16 v[60:63], v[192:195], v[216:219], v[60:63]
	v_mfma_f32_16x16x32_f16 v[48:51], v[150:153], v[224:227], v[48:51]
	v_mfma_f32_16x16x32_f16 v[44:47], v[192:195], v[224:227], v[44:47]
	v_mfma_f32_16x16x32_f16 v[32:35], v[150:153], v[232:235], v[32:35]
	v_mfma_f32_16x16x32_f16 v[28:31], v[192:195], v[232:235], v[28:31]
	v_mfma_f32_16x16x32_f16 v[16:19], v[150:153], v[240:243], v[16:19]
	v_mfma_f32_16x16x32_f16 v[12:15], v[192:195], v[240:243], v[12:15]
	s_setprio 0
	s_setprio 1
	v_mfma_f32_16x16x32_f16 v[56:59], v[196:199], v[212:215], v[56:59]
	v_mfma_f32_16x16x32_f16 v[52:55], v[204:207], v[212:215], v[52:55]
	v_mfma_f32_16x16x32_f16 v[40:43], v[196:199], v[220:223], v[40:43]
	v_mfma_f32_16x16x32_f16 v[36:39], v[204:207], v[220:223], v[36:39]
	v_mfma_f32_16x16x32_f16 v[24:27], v[196:199], v[228:231], v[24:27]
	v_mfma_f32_16x16x32_f16 v[20:23], v[204:207], v[228:231], v[20:23]
	v_mfma_f32_16x16x32_f16 v[8:11], v[196:199], v[236:239], v[8:11]
	v_mfma_f32_16x16x32_f16 v[4:7], v[204:207], v[236:239], v[4:7]
	v_mfma_f32_16x16x32_f16 v[56:59], v[200:203], v[216:219], v[56:59]
	v_mfma_f32_16x16x32_f16 v[52:55], v[208:211], v[216:219], v[52:55]
	v_mfma_f32_16x16x32_f16 v[40:43], v[200:203], v[224:227], v[40:43]
	v_mfma_f32_16x16x32_f16 v[36:39], v[208:211], v[224:227], v[36:39]
	v_mfma_f32_16x16x32_f16 v[24:27], v[200:203], v[232:235], v[24:27]
	v_mfma_f32_16x16x32_f16 v[20:23], v[208:211], v[232:235], v[20:23]
	v_mfma_f32_16x16x32_f16 v[8:11], v[200:203], v[240:243], v[8:11]
	v_mfma_f32_16x16x32_f16 v[4:7], v[208:211], v[240:243], v[4:7]
	s_setprio 0
	s_barrier
	s_add_i32 s12, s12, 2
	s_add_u32 s54, s54, 0x100
	s_addc_u32 s55, s55, 0
	s_add_u32 s10, s10, 0x100
	s_addc_u32 s11, s11, 0
	s_cmp_gt_u32 s12, 13
	s_cbranch_scc0 .LBB0_1074
	s_and_b64 vcc, exec, s[44:45]
	s_cbranch_vccz .LBB0_1077
	s_barrier
